# PEER act sub-phase unrolled over the wave's 8 tokens with all LDS reads and table gathers requested up front
# baseline (speedup 1.0000x reference)
; #define LAS __attribute__((address_space(3)))
; __global__ void __launch_bounds__(NTHR, 2) k_main(Args a) {
;     ...
;             for (int it = 0; it < 8; ++it) {
;                 const int tl = it * 8 + wave, t = j * 64 + tl;
;                 const unsigned ew = *(const LAS unsigned*)(EL + tl * 128 + 2 * lane); const int e0 = (int)(ew & 0xffffu), e1 = (int)(ew >> 16);
;                 typedef int i2v __attribute__((ext_vector_type(2))); const i2v si = *(const LAS i2v*)(ACC + tl * 128 + 2 * lane);
;                 typedef float f2v __attribute__((ext_vector_type(2))); const f2v gt = *(const LAS f2v*)(GL + tl * 128 + 2 * lane); const float xs = XS[t];
;                 const int sx = ((const int*)(XS + T))[t];
;                 const float z0 = (float)(2 * si.x + sx) * SU[e0] * xs, z1 = (float)(2 * si.y + sx) * SU[e1] * xs;
;                 const float a0 = gt.x * gelu_as(z0) * SV[e0], a1 = gt.y * gelu_as(z1) * SV[e1];
.LBB0_674:
	s_ashr_i32 s41, s40, 31
	s_lshl_b64 s[10:11], s[40:41], 2
	s_add_u32 s14, s90, s10
	s_addc_u32 s15, s91, s11
	v_readlane_b32 s42, v235, 36
	v_readlane_b32 s43, v235, 37
	v_readlane_b32 s44, v235, 38
	v_readlane_b32 s45, v235, 39
	v_add_u32_e32 v74, 0x16000, v91
	ds_read_b32 v18, v92
	ds_read_b32 v19, v92 offset:2048
	ds_read_b32 v20, v92 offset:4096
	ds_read_b32 v21, v92 offset:6144
	ds_read_b32 v22, v92 offset:8192
	ds_read_b32 v23, v92 offset:10240
	ds_read_b32 v24, v92 offset:12288
	ds_read_b32 v25, v92 offset:14336
	ds_read_b64 v[26:27], v91
	ds_read_b64 v[42:43], v74
	ds_read_b64 v[28:29], v91 offset:4096
	ds_read_b64 v[44:45], v74 offset:4096
	ds_read_b64 v[30:31], v91 offset:8192
	ds_read_b64 v[46:47], v74 offset:8192
	ds_read_b64 v[32:33], v91 offset:12288
	ds_read_b64 v[48:49], v74 offset:12288
	ds_read_b64 v[34:35], v91 offset:16384
	ds_read_b64 v[50:51], v74 offset:16384
	ds_read_b64 v[36:37], v91 offset:20480
	ds_read_b64 v[52:53], v74 offset:20480
	ds_read_b64 v[38:39], v91 offset:24576
	ds_read_b64 v[54:55], v74 offset:24576
	ds_read_b64 v[40:41], v91 offset:28672
	ds_read_b64 v[56:57], v74 offset:28672
	global_load_dword v58, v109, s[14:15]
	global_load_dword v66, v108, s[14:15]
	global_load_dword v59, v109, s[14:15] offset:32
	global_load_dword v67, v108, s[14:15] offset:32
	global_load_dword v60, v109, s[14:15] offset:64
	global_load_dword v68, v108, s[14:15] offset:64
	global_load_dword v61, v109, s[14:15] offset:96
	global_load_dword v69, v108, s[14:15] offset:96
	global_load_dword v62, v109, s[14:15] offset:128
	global_load_dword v70, v108, s[14:15] offset:128
	global_load_dword v63, v109, s[14:15] offset:160
	global_load_dword v71, v108, s[14:15] offset:160
	global_load_dword v64, v109, s[14:15] offset:192
	global_load_dword v72, v108, s[14:15] offset:192
	global_load_dword v65, v109, s[14:15] offset:224
	global_load_dword v73, v108, s[14:15] offset:224
	s_waitcnt lgkmcnt(0)
	v_lshlrev_b32_sdwa v75, v120, v18 dst_sel:DWORD dst_unused:UNUSED_PAD src0_sel:DWORD src1_sel:WORD_0
	v_lshlrev_b32_sdwa v76, v120, v18 dst_sel:DWORD dst_unused:UNUSED_PAD src0_sel:DWORD src1_sel:WORD_1
	s_nop 1
	global_load_dword v122, v75, s[42:43]
	global_load_dword v130, v76, s[42:43]
	global_load_dword v138, v76, s[44:45]
	global_load_dword v146, v75, s[44:45]
	v_lshlrev_b32_sdwa v75, v120, v19 dst_sel:DWORD dst_unused:UNUSED_PAD src0_sel:DWORD src1_sel:WORD_0
	v_lshlrev_b32_sdwa v76, v120, v19 dst_sel:DWORD dst_unused:UNUSED_PAD src0_sel:DWORD src1_sel:WORD_1
	s_nop 1
	global_load_dword v123, v75, s[42:43]
	global_load_dword v131, v76, s[42:43]
	global_load_dword v139, v76, s[44:45]
	global_load_dword v147, v75, s[44:45]
	v_lshlrev_b32_sdwa v75, v120, v20 dst_sel:DWORD dst_unused:UNUSED_PAD src0_sel:DWORD src1_sel:WORD_0
	v_lshlrev_b32_sdwa v76, v120, v20 dst_sel:DWORD dst_unused:UNUSED_PAD src0_sel:DWORD src1_sel:WORD_1
	s_nop 1
	global_load_dword v124, v75, s[42:43]
	global_load_dword v132, v76, s[42:43]
	global_load_dword v140, v76, s[44:45]
	global_load_dword v148, v75, s[44:45]
	v_lshlrev_b32_sdwa v75, v120, v21 dst_sel:DWORD dst_unused:UNUSED_PAD src0_sel:DWORD src1_sel:WORD_0
	v_lshlrev_b32_sdwa v76, v120, v21 dst_sel:DWORD dst_unused:UNUSED_PAD src0_sel:DWORD src1_sel:WORD_1
	s_nop 1
	global_load_dword v125, v75, s[42:43]
	global_load_dword v133, v76, s[42:43]
	global_load_dword v141, v76, s[44:45]
	global_load_dword v149, v75, s[44:45]
	v_lshlrev_b32_sdwa v75, v120, v22 dst_sel:DWORD dst_unused:UNUSED_PAD src0_sel:DWORD src1_sel:WORD_0
	v_lshlrev_b32_sdwa v76, v120, v22 dst_sel:DWORD dst_unused:UNUSED_PAD src0_sel:DWORD src1_sel:WORD_1
	s_nop 1
	global_load_dword v126, v75, s[42:43]
	global_load_dword v134, v76, s[42:43]
	global_load_dword v142, v76, s[44:45]
	global_load_dword v150, v75, s[44:45]
	v_lshlrev_b32_sdwa v75, v120, v23 dst_sel:DWORD dst_unused:UNUSED_PAD src0_sel:DWORD src1_sel:WORD_0
	v_lshlrev_b32_sdwa v76, v120, v23 dst_sel:DWORD dst_unused:UNUSED_PAD src0_sel:DWORD src1_sel:WORD_1
	s_nop 1
	global_load_dword v127, v75, s[42:43]
	global_load_dword v135, v76, s[42:43]
	global_load_dword v143, v76, s[44:45]
	global_load_dword v151, v75, s[44:45]
	v_lshlrev_b32_sdwa v75, v120, v24 dst_sel:DWORD dst_unused:UNUSED_PAD src0_sel:DWORD src1_sel:WORD_0
	v_lshlrev_b32_sdwa v76, v120, v24 dst_sel:DWORD dst_unused:UNUSED_PAD src0_sel:DWORD src1_sel:WORD_1
	s_nop 1
	global_load_dword v128, v75, s[42:43]
	global_load_dword v136, v76, s[42:43]
	global_load_dword v144, v76, s[44:45]
	global_load_dword v152, v75, s[44:45]
	v_lshlrev_b32_sdwa v75, v120, v25 dst_sel:DWORD dst_unused:UNUSED_PAD src0_sel:DWORD src1_sel:WORD_0
	v_lshlrev_b32_sdwa v76, v120, v25 dst_sel:DWORD dst_unused:UNUSED_PAD src0_sel:DWORD src1_sel:WORD_1
	s_nop 1
	global_load_dword v129, v75, s[42:43]
	global_load_dword v137, v76, s[42:43]
	global_load_dword v145, v76, s[44:45]
	global_load_dword v153, v75, s[44:45]
	s_waitcnt vmcnt(28)
; #define LAS __attribute__((address_space(3)))
; __global__ void __launch_bounds__(NTHR, 2) k_main(Args a) {
;     ...
;                 const unsigned ew = *(const LAS unsigned*)(EL + tl * 128 + 2 * lane); const int e0 = (int)(ew & 0xffffu), e1 = (int)(ew >> 16);
;                 typedef int i2v __attribute__((ext_vector_type(2))); const i2v si = *(const LAS i2v*)(ACC + tl * 128 + 2 * lane);
;                 typedef float f2v __attribute__((ext_vector_type(2))); const f2v gt = *(const LAS f2v*)(GL + tl * 128 + 2 * lane); const float xs = XS[t];
;                 const int sx = ((const int*)(XS + T))[t];
;                 const float z0 = (float)(2 * si.x + sx) * SU[e0] * xs, z1 = (float)(2 * si.y + sx) * SU[e1] * xs;
;                 const float a0 = gt.x * gelu_as(z0) * SV[e0], a1 = gt.y * gelu_as(z1) * SV[e1];
;                 const float mx = wave_max_dpp(fmaxf(fabsf(a0), fabsf(a1)));
;                 const float sc = mx > 0.f ? mx * (1.f / 119.f) : 1.f, inv = 1.f / sc;
;                 const int q0 = (int)rintf(a0 * inv), q1 = (int)rintf(a1 * inv);
;                 *(LAS unsigned short*)(AL + tl * 128 + 2 * lane) = (unsigned short)((q0 & 255) | ((q1 & 255) << 8));
;                 const int qs = wave_sum_dpp_i(q0 + q1);
;                 if (lane == 0) { ASC[tl] = sc; SAL[tl] = qs; }
	v_lshl_add_u32 v154, v26, 1, v58
	v_lshl_add_u32 v155, v27, 1, v58
	v_cvt_f32_i32_e32 v154, v154
	v_cvt_f32_i32_e32 v155, v155
	v_mul_f32_e32 v154, v122, v154
	v_mul_f32_e32 v155, v130, v155
	v_mul_f32_e32 v154, v66, v154
	v_mul_f32_e32 v155, v66, v155
	v_mul_f32_e64 v156, |v154|, s82
	v_mul_f32_e64 v157, |v155|, s82
	v_fma_f32 v158, v156, s83, 1.0
	v_fma_f32 v159, v157, s83, 1.0
	v_rcp_f32_e32 v158, v158
	v_rcp_f32_e32 v159, v159
	v_mul_f32_e64 v156, v156, -v156
	v_mul_f32_e64 v157, v157, -v157
	v_mul_f32_e32 v156, 0x3fb8aa3b, v156
	v_mul_f32_e32 v157, 0x3fb8aa3b, v157
	v_fmamk_f32 v160, v158, 0x3f87dc22, v110
	v_fmamk_f32 v161, v159, 0x3f87dc22, v110
	v_exp_f32_e32 v156, v156
	v_exp_f32_e32 v157, v157
	v_fmaak_f32 v160, v158, v160, 0x3fb5f0e3
	v_fmaak_f32 v161, v159, v161, 0x3fb5f0e3
	v_fmaak_f32 v160, v158, v160, 0xbe91a98e
	v_fmaak_f32 v161, v159, v161, 0xbe91a98e
	v_fmaak_f32 v160, v158, v160, 0x3e827906
	v_fmaak_f32 v161, v159, v161, 0x3e827906
	v_mul_f32_e32 v158, v158, v160
	v_mul_f32_e32 v159, v159, v161
	v_fma_f32 v156, -v156, v158, 1.0
	v_fma_f32 v157, -v157, v159, 1.0
	v_mul_f32_e32 v162, 0.5, v154
	v_mul_f32_e32 v163, 0.5, v155
	v_bfi_b32 v154, s84, v156, v154
	v_bfi_b32 v155, s84, v157, v155
	v_add_f32_e32 v154, 1.0, v154
	v_add_f32_e32 v155, 1.0, v155
	v_mul_f32_e32 v154, v162, v154
	v_mul_f32_e32 v155, v163, v155
	v_mul_f32_e32 v154, v42, v154
	v_mul_f32_e32 v155, v43, v155
	v_mul_f32_e32 v154, v146, v154
	v_mul_f32_e32 v155, v138, v155
	v_max_f32_e64 v164, |v154|, |v155|
	s_nop 1
	v_max_f32_dpp v164, v164, v164 quad_perm:[1,0,3,2] row_mask:0xf bank_mask:0xf
	s_nop 1
	v_max_f32_dpp v164, v164, v164 quad_perm:[2,3,0,1] row_mask:0xf bank_mask:0xf
	s_nop 1
	v_max_f32_dpp v164, v164, v164 row_half_mirror row_mask:0xf bank_mask:0xf
	s_nop 1
	v_max_f32_dpp v164, v164, v164 row_mirror row_mask:0xf bank_mask:0xf
	s_nop 1
	v_readlane_b32 s46, v164, 32
	v_readlane_b32 s47, v164, 48
	v_readlane_b32 s12, v164, 0
	v_readlane_b32 s13, v164, 16
	s_nop 1
	v_mov_b32_e32 v164, s47
	v_max_f32_e32 v164, s46, v164
	v_mov_b32_e32 v165, s13
	v_max3_f32 v164, s12, v165, v164
	v_mul_f32_e32 v165, 0x3c09ae41, v164
	v_cmp_lt_f32_e32 vcc, 0, v164
	s_nop 1
	v_cndmask_b32_e32 v164, 1.0, v165, vcc
	v_div_scale_f32 v166, s[12:13], v164, v164, 1.0
	v_rcp_f32_e32 v167, v166
	v_div_scale_f32 v168, vcc, 1.0, v164, 1.0
	v_fma_f32 v169, -v166, v167, 1.0
	v_fmac_f32_e32 v167, v169, v167
	v_mul_f32_e32 v169, v168, v167
	v_fma_f32 v170, -v166, v169, v168
	v_fmac_f32_e32 v169, v170, v167
	v_fma_f32 v166, -v166, v169, v168
	v_div_fmas_f32 v166, v166, v167, v169
	v_div_fixup_f32 v166, v166, v164, 1.0
	v_mul_f32_e32 v154, v166, v154
	v_mul_f32_e32 v155, v166, v155
	v_rndne_f32_e32 v154, v154
	v_rndne_f32_e32 v155, v155
	v_cvt_i32_f32_e32 v154, v154
	v_cvt_i32_f32_e32 v155, v155
	v_perm_b32 v167, v155, v154, s85
	v_add_u32_e32 v154, v154, v155
	ds_write_b16 v90, v167
	s_nop 1
	v_add_u32_dpp v154, v154, v154 quad_perm:[1,0,3,2] row_mask:0xf bank_mask:0xf bound_ctrl:1
	s_nop 1
	v_add_u32_dpp v154, v154, v154 quad_perm:[2,3,0,1] row_mask:0xf bank_mask:0xf bound_ctrl:1
	s_nop 1
	v_add_u32_dpp v154, v154, v154 row_half_mirror row_mask:0xf bank_mask:0xf bound_ctrl:1
	s_nop 1
	v_add_u32_dpp v154, v154, v154 row_mirror row_mask:0xf bank_mask:0xf bound_ctrl:1
	s_nop 1
	v_readlane_b32 s46, v154, 0
	v_readlane_b32 s47, v154, 16
	v_readlane_b32 s12, v154, 32
	v_readlane_b32 s13, v154, 48
	s_nop 1
	s_add_i32 s46, s47, s46
	s_add_i32 s46, s46, s12
	s_add_i32 s46, s46, s13
	s_mov_b32 s47, s67
	s_and_saveexec_b64 s[12:13], s[8:9]
	v_mov_b32_e32 v154, s47
	v_mov_b32_e32 v155, s46
	ds_write2st64_b32 v154, v164, v155 offset1:1
	s_or_b64 exec, exec, s[12:13]
	s_waitcnt vmcnt(24)
	v_lshl_add_u32 v154, v28, 1, v59
	v_lshl_add_u32 v155, v29, 1, v59
	v_cvt_f32_i32_e32 v154, v154
	v_cvt_f32_i32_e32 v155, v155
	v_mul_f32_e32 v154, v123, v154
	v_mul_f32_e32 v155, v131, v155
	v_mul_f32_e32 v154, v67, v154
	v_mul_f32_e32 v155, v67, v155
	v_mul_f32_e64 v156, |v154|, s82
	v_mul_f32_e64 v157, |v155|, s82
	v_fma_f32 v158, v156, s83, 1.0
	v_fma_f32 v159, v157, s83, 1.0
	v_rcp_f32_e32 v158, v158
	v_rcp_f32_e32 v159, v159
	v_mul_f32_e64 v156, v156, -v156
	v_mul_f32_e64 v157, v157, -v157
	v_mul_f32_e32 v156, 0x3fb8aa3b, v156
	v_mul_f32_e32 v157, 0x3fb8aa3b, v157
	v_fmamk_f32 v160, v158, 0x3f87dc22, v110
	v_fmamk_f32 v161, v159, 0x3f87dc22, v110
	v_exp_f32_e32 v156, v156
	v_exp_f32_e32 v157, v157
	v_fmaak_f32 v160, v158, v160, 0x3fb5f0e3
	v_fmaak_f32 v161, v159, v161, 0x3fb5f0e3
	v_fmaak_f32 v160, v158, v160, 0xbe91a98e
	v_fmaak_f32 v161, v159, v161, 0xbe91a98e
	v_fmaak_f32 v160, v158, v160, 0x3e827906
	v_fmaak_f32 v161, v159, v161, 0x3e827906
	v_mul_f32_e32 v158, v158, v160
	v_mul_f32_e32 v159, v159, v161
	v_fma_f32 v156, -v156, v158, 1.0
	v_fma_f32 v157, -v157, v159, 1.0
	v_mul_f32_e32 v162, 0.5, v154
	v_mul_f32_e32 v163, 0.5, v155
	v_bfi_b32 v154, s84, v156, v154
	v_bfi_b32 v155, s84, v157, v155
	v_add_f32_e32 v154, 1.0, v154
	v_add_f32_e32 v155, 1.0, v155
	v_mul_f32_e32 v154, v162, v154
	v_mul_f32_e32 v155, v163, v155
	v_mul_f32_e32 v154, v44, v154
	v_mul_f32_e32 v155, v45, v155
	v_mul_f32_e32 v154, v147, v154
	v_mul_f32_e32 v155, v139, v155
	v_max_f32_e64 v164, |v154|, |v155|
	s_nop 1
	v_max_f32_dpp v164, v164, v164 quad_perm:[1,0,3,2] row_mask:0xf bank_mask:0xf
	s_nop 1
	v_max_f32_dpp v164, v164, v164 quad_perm:[2,3,0,1] row_mask:0xf bank_mask:0xf
	s_nop 1
	v_max_f32_dpp v164, v164, v164 row_half_mirror row_mask:0xf bank_mask:0xf
	s_nop 1
	v_max_f32_dpp v164, v164, v164 row_mirror row_mask:0xf bank_mask:0xf
	s_nop 1
	v_readlane_b32 s46, v164, 32
	v_readlane_b32 s47, v164, 48
	v_readlane_b32 s12, v164, 0
; #define LAS __attribute__((address_space(3)))
; __global__ void __launch_bounds__(NTHR, 2) k_main(Args a) {
;     ...
;             for (int it = 0; it < 8; ++it) {
;                 const int tl = it * 8 + wave, t = j * 64 + tl;
;                 const unsigned ew = *(const LAS unsigned*)(EL + tl * 128 + 2 * lane); const int e0 = (int)(ew & 0xffffu), e1 = (int)(ew >> 16);
;                 typedef int i2v __attribute__((ext_vector_type(2))); const i2v si = *(const LAS i2v*)(ACC + tl * 128 + 2 * lane);
;                 typedef float f2v __attribute__((ext_vector_type(2))); const f2v gt = *(const LAS f2v*)(GL + tl * 128 + 2 * lane); const float xs = XS[t];
;                 const int sx = ((const int*)(XS + T))[t];
;                 const float z0 = (float)(2 * si.x + sx) * SU[e0] * xs, z1 = (float)(2 * si.y + sx) * SU[e1] * xs;
;                 const float a0 = gt.x * gelu_as(z0) * SV[e0], a1 = gt.y * gelu_as(z1) * SV[e1];
;                 const float mx = wave_max_dpp(fmaxf(fabsf(a0), fabsf(a1)));
;                 const float sc = mx > 0.f ? mx * (1.f / 119.f) : 1.f, inv = 1.f / sc;
;                 const int q0 = (int)rintf(a0 * inv), q1 = (int)rintf(a1 * inv);
;                 *(LAS unsigned short*)(AL + tl * 128 + 2 * lane) = (unsigned short)((q0 & 255) | ((q1 & 255) << 8));
;                 const int qs = wave_sum_dpp_i(q0 + q1);
;                 if (lane == 0) { ASC[tl] = sc; SAL[tl] = qs; }
;             }
	v_readlane_b32 s13, v164, 16
	s_nop 1
	v_mov_b32_e32 v164, s47
	v_max_f32_e32 v164, s46, v164
	v_mov_b32_e32 v165, s13
	v_max3_f32 v164, s12, v165, v164
	v_mul_f32_e32 v165, 0x3c09ae41, v164
	v_cmp_lt_f32_e32 vcc, 0, v164
	s_nop 1
	v_cndmask_b32_e32 v164, 1.0, v165, vcc
	v_div_scale_f32 v166, s[12:13], v164, v164, 1.0
	v_rcp_f32_e32 v167, v166
	v_div_scale_f32 v168, vcc, 1.0, v164, 1.0
	v_fma_f32 v169, -v166, v167, 1.0
	v_fmac_f32_e32 v167, v169, v167
	v_mul_f32_e32 v169, v168, v167
	v_fma_f32 v170, -v166, v169, v168
	v_fmac_f32_e32 v169, v170, v167
	v_fma_f32 v166, -v166, v169, v168
	v_div_fmas_f32 v166, v166, v167, v169
	v_div_fixup_f32 v166, v166, v164, 1.0
	v_mul_f32_e32 v154, v166, v154
	v_mul_f32_e32 v155, v166, v155
	v_rndne_f32_e32 v154, v154
	v_rndne_f32_e32 v155, v155
	v_cvt_i32_f32_e32 v154, v154
	v_cvt_i32_f32_e32 v155, v155
	v_perm_b32 v167, v155, v154, s85
	v_add_u32_e32 v154, v154, v155
	ds_write_b16 v90, v167 offset:1024
	s_nop 1
	v_add_u32_dpp v154, v154, v154 quad_perm:[1,0,3,2] row_mask:0xf bank_mask:0xf bound_ctrl:1
	s_nop 1
	v_add_u32_dpp v154, v154, v154 quad_perm:[2,3,0,1] row_mask:0xf bank_mask:0xf bound_ctrl:1
	s_nop 1
	v_add_u32_dpp v154, v154, v154 row_half_mirror row_mask:0xf bank_mask:0xf bound_ctrl:1
	s_nop 1
	v_add_u32_dpp v154, v154, v154 row_mirror row_mask:0xf bank_mask:0xf bound_ctrl:1
	s_nop 1
	v_readlane_b32 s46, v154, 0
	v_readlane_b32 s47, v154, 16
	v_readlane_b32 s12, v154, 32
	v_readlane_b32 s13, v154, 48
	s_nop 1
	s_add_i32 s46, s47, s46
	s_add_i32 s46, s46, s12
	s_add_i32 s46, s46, s13
	s_add_i32 s47, s67, 32
	s_and_saveexec_b64 s[12:13], s[8:9]
	v_mov_b32_e32 v154, s47
	v_mov_b32_e32 v155, s46
	ds_write2st64_b32 v154, v164, v155 offset1:1
	s_or_b64 exec, exec, s[12:13]
	s_waitcnt vmcnt(20)
	v_lshl_add_u32 v154, v30, 1, v60
	v_lshl_add_u32 v155, v31, 1, v60
	v_cvt_f32_i32_e32 v154, v154
	v_cvt_f32_i32_e32 v155, v155
	v_mul_f32_e32 v154, v124, v154
	v_mul_f32_e32 v155, v132, v155
	v_mul_f32_e32 v154, v68, v154
	v_mul_f32_e32 v155, v68, v155
	v_mul_f32_e64 v156, |v154|, s82
	v_mul_f32_e64 v157, |v155|, s82
	v_fma_f32 v158, v156, s83, 1.0
	v_fma_f32 v159, v157, s83, 1.0
	v_rcp_f32_e32 v158, v158
	v_rcp_f32_e32 v159, v159
	v_mul_f32_e64 v156, v156, -v156
	v_mul_f32_e64 v157, v157, -v157
	v_mul_f32_e32 v156, 0x3fb8aa3b, v156
	v_mul_f32_e32 v157, 0x3fb8aa3b, v157
	v_fmamk_f32 v160, v158, 0x3f87dc22, v110
	v_fmamk_f32 v161, v159, 0x3f87dc22, v110
	v_exp_f32_e32 v156, v156
	v_exp_f32_e32 v157, v157
	v_fmaak_f32 v160, v158, v160, 0x3fb5f0e3
	v_fmaak_f32 v161, v159, v161, 0x3fb5f0e3
	v_fmaak_f32 v160, v158, v160, 0xbe91a98e
	v_fmaak_f32 v161, v159, v161, 0xbe91a98e
	v_fmaak_f32 v160, v158, v160, 0x3e827906
	v_fmaak_f32 v161, v159, v161, 0x3e827906
	v_mul_f32_e32 v158, v158, v160
	v_mul_f32_e32 v159, v159, v161
	v_fma_f32 v156, -v156, v158, 1.0
	v_fma_f32 v157, -v157, v159, 1.0
	v_mul_f32_e32 v162, 0.5, v154
	v_mul_f32_e32 v163, 0.5, v155
	v_bfi_b32 v154, s84, v156, v154
	v_bfi_b32 v155, s84, v157, v155
	v_add_f32_e32 v154, 1.0, v154
	v_add_f32_e32 v155, 1.0, v155
	v_mul_f32_e32 v154, v162, v154
	v_mul_f32_e32 v155, v163, v155
	v_mul_f32_e32 v154, v46, v154
	v_mul_f32_e32 v155, v47, v155
	v_mul_f32_e32 v154, v148, v154
	v_mul_f32_e32 v155, v140, v155
	v_max_f32_e64 v164, |v154|, |v155|
	s_nop 1
	v_max_f32_dpp v164, v164, v164 quad_perm:[1,0,3,2] row_mask:0xf bank_mask:0xf
	s_nop 1
	v_max_f32_dpp v164, v164, v164 quad_perm:[2,3,0,1] row_mask:0xf bank_mask:0xf
	s_nop 1
	v_max_f32_dpp v164, v164, v164 row_half_mirror row_mask:0xf bank_mask:0xf
	s_nop 1
	v_max_f32_dpp v164, v164, v164 row_mirror row_mask:0xf bank_mask:0xf
	s_nop 1
	v_readlane_b32 s46, v164, 32
	v_readlane_b32 s47, v164, 48
	v_readlane_b32 s12, v164, 0
	v_readlane_b32 s13, v164, 16
	s_nop 1
	v_mov_b32_e32 v164, s47
	v_max_f32_e32 v164, s46, v164
	v_mov_b32_e32 v165, s13
	v_max3_f32 v164, s12, v165, v164
	v_mul_f32_e32 v165, 0x3c09ae41, v164
	v_cmp_lt_f32_e32 vcc, 0, v164
	s_nop 1
	v_cndmask_b32_e32 v164, 1.0, v165, vcc
	v_div_scale_f32 v166, s[12:13], v164, v164, 1.0
	v_rcp_f32_e32 v167, v166
	v_div_scale_f32 v168, vcc, 1.0, v164, 1.0
	v_fma_f32 v169, -v166, v167, 1.0
	v_fmac_f32_e32 v167, v169, v167
	v_mul_f32_e32 v169, v168, v167
	v_fma_f32 v170, -v166, v169, v168
	v_fmac_f32_e32 v169, v170, v167
	v_fma_f32 v166, -v166, v169, v168
	v_div_fmas_f32 v166, v166, v167, v169
	v_div_fixup_f32 v166, v166, v164, 1.0
	v_mul_f32_e32 v154, v166, v154
	v_mul_f32_e32 v155, v166, v155
	v_rndne_f32_e32 v154, v154
	v_rndne_f32_e32 v155, v155
	v_cvt_i32_f32_e32 v154, v154
	v_cvt_i32_f32_e32 v155, v155
	v_perm_b32 v167, v155, v154, s85
	v_add_u32_e32 v154, v154, v155
	ds_write_b16 v90, v167 offset:2048
	s_nop 1
	v_add_u32_dpp v154, v154, v154 quad_perm:[1,0,3,2] row_mask:0xf bank_mask:0xf bound_ctrl:1
	s_nop 1
	v_add_u32_dpp v154, v154, v154 quad_perm:[2,3,0,1] row_mask:0xf bank_mask:0xf bound_ctrl:1
	s_nop 1
	v_add_u32_dpp v154, v154, v154 row_half_mirror row_mask:0xf bank_mask:0xf bound_ctrl:1
	s_nop 1
	v_add_u32_dpp v154, v154, v154 row_mirror row_mask:0xf bank_mask:0xf bound_ctrl:1
	s_nop 1
	v_readlane_b32 s46, v154, 0
	v_readlane_b32 s47, v154, 16
	v_readlane_b32 s12, v154, 32
	v_readlane_b32 s13, v154, 48
	s_nop 1
	s_add_i32 s46, s47, s46
	s_add_i32 s46, s46, s12
	s_add_i32 s46, s46, s13
	s_add_i32 s47, s67, 64
	s_and_saveexec_b64 s[12:13], s[8:9]
	v_mov_b32_e32 v154, s47
	v_mov_b32_e32 v155, s46
	ds_write2st64_b32 v154, v164, v155 offset1:1
	s_or_b64 exec, exec, s[12:13]
	s_waitcnt vmcnt(16)
; #define LAS __attribute__((address_space(3)))
; __global__ void __launch_bounds__(NTHR, 2) k_main(Args a) {
;     ...
;             for (int it = 0; it < 8; ++it) {
;                 const int tl = it * 8 + wave, t = j * 64 + tl;
;                 const unsigned ew = *(const LAS unsigned*)(EL + tl * 128 + 2 * lane); const int e0 = (int)(ew & 0xffffu), e1 = (int)(ew >> 16);
;                 typedef int i2v __attribute__((ext_vector_type(2))); const i2v si = *(const LAS i2v*)(ACC + tl * 128 + 2 * lane);
;                 typedef float f2v __attribute__((ext_vector_type(2))); const f2v gt = *(const LAS f2v*)(GL + tl * 128 + 2 * lane); const float xs = XS[t];
;                 const int sx = ((const int*)(XS + T))[t];
;                 const float z0 = (float)(2 * si.x + sx) * SU[e0] * xs, z1 = (float)(2 * si.y + sx) * SU[e1] * xs;
;                 const float a0 = gt.x * gelu_as(z0) * SV[e0], a1 = gt.y * gelu_as(z1) * SV[e1];
;                 const float mx = wave_max_dpp(fmaxf(fabsf(a0), fabsf(a1)));
;                 const float sc = mx > 0.f ? mx * (1.f / 119.f) : 1.f, inv = 1.f / sc;
;                 const int q0 = (int)rintf(a0 * inv), q1 = (int)rintf(a1 * inv);
;                 *(LAS unsigned short*)(AL + tl * 128 + 2 * lane) = (unsigned short)((q0 & 255) | ((q1 & 255) << 8));
;                 const int qs = wave_sum_dpp_i(q0 + q1);
;                 if (lane == 0) { ASC[tl] = sc; SAL[tl] = qs; }
;             }
	v_lshl_add_u32 v154, v32, 1, v61
	v_lshl_add_u32 v155, v33, 1, v61
	v_cvt_f32_i32_e32 v154, v154
	v_cvt_f32_i32_e32 v155, v155
	v_mul_f32_e32 v154, v125, v154
	v_mul_f32_e32 v155, v133, v155
	v_mul_f32_e32 v154, v69, v154
	v_mul_f32_e32 v155, v69, v155
	v_mul_f32_e64 v156, |v154|, s82
	v_mul_f32_e64 v157, |v155|, s82
	v_fma_f32 v158, v156, s83, 1.0
	v_fma_f32 v159, v157, s83, 1.0
	v_rcp_f32_e32 v158, v158
	v_rcp_f32_e32 v159, v159
	v_mul_f32_e64 v156, v156, -v156
	v_mul_f32_e64 v157, v157, -v157
	v_mul_f32_e32 v156, 0x3fb8aa3b, v156
	v_mul_f32_e32 v157, 0x3fb8aa3b, v157
	v_fmamk_f32 v160, v158, 0x3f87dc22, v110
	v_fmamk_f32 v161, v159, 0x3f87dc22, v110
	v_exp_f32_e32 v156, v156
	v_exp_f32_e32 v157, v157
	v_fmaak_f32 v160, v158, v160, 0x3fb5f0e3
	v_fmaak_f32 v161, v159, v161, 0x3fb5f0e3
	v_fmaak_f32 v160, v158, v160, 0xbe91a98e
	v_fmaak_f32 v161, v159, v161, 0xbe91a98e
	v_fmaak_f32 v160, v158, v160, 0x3e827906
	v_fmaak_f32 v161, v159, v161, 0x3e827906
	v_mul_f32_e32 v158, v158, v160
	v_mul_f32_e32 v159, v159, v161
	v_fma_f32 v156, -v156, v158, 1.0
	v_fma_f32 v157, -v157, v159, 1.0
	v_mul_f32_e32 v162, 0.5, v154
	v_mul_f32_e32 v163, 0.5, v155
	v_bfi_b32 v154, s84, v156, v154
	v_bfi_b32 v155, s84, v157, v155
	v_add_f32_e32 v154, 1.0, v154
	v_add_f32_e32 v155, 1.0, v155
	v_mul_f32_e32 v154, v162, v154
	v_mul_f32_e32 v155, v163, v155
	v_mul_f32_e32 v154, v48, v154
	v_mul_f32_e32 v155, v49, v155
	v_mul_f32_e32 v154, v149, v154
	v_mul_f32_e32 v155, v141, v155
	v_max_f32_e64 v164, |v154|, |v155|
	s_nop 1
	v_max_f32_dpp v164, v164, v164 quad_perm:[1,0,3,2] row_mask:0xf bank_mask:0xf
	s_nop 1
	v_max_f32_dpp v164, v164, v164 quad_perm:[2,3,0,1] row_mask:0xf bank_mask:0xf
	s_nop 1
	v_max_f32_dpp v164, v164, v164 row_half_mirror row_mask:0xf bank_mask:0xf
	s_nop 1
	v_max_f32_dpp v164, v164, v164 row_mirror row_mask:0xf bank_mask:0xf
	s_nop 1
	v_readlane_b32 s46, v164, 32
	v_readlane_b32 s47, v164, 48
	v_readlane_b32 s12, v164, 0
	v_readlane_b32 s13, v164, 16
	s_nop 1
	v_mov_b32_e32 v164, s47
	v_max_f32_e32 v164, s46, v164
	v_mov_b32_e32 v165, s13
	v_max3_f32 v164, s12, v165, v164
	v_mul_f32_e32 v165, 0x3c09ae41, v164
	v_cmp_lt_f32_e32 vcc, 0, v164
	s_nop 1
	v_cndmask_b32_e32 v164, 1.0, v165, vcc
	v_div_scale_f32 v166, s[12:13], v164, v164, 1.0
	v_rcp_f32_e32 v167, v166
	v_div_scale_f32 v168, vcc, 1.0, v164, 1.0
	v_fma_f32 v169, -v166, v167, 1.0
	v_fmac_f32_e32 v167, v169, v167
	v_mul_f32_e32 v169, v168, v167
	v_fma_f32 v170, -v166, v169, v168
	v_fmac_f32_e32 v169, v170, v167
	v_fma_f32 v166, -v166, v169, v168
	v_div_fmas_f32 v166, v166, v167, v169
	v_div_fixup_f32 v166, v166, v164, 1.0
	v_mul_f32_e32 v154, v166, v154
	v_mul_f32_e32 v155, v166, v155
	v_rndne_f32_e32 v154, v154
	v_rndne_f32_e32 v155, v155
	v_cvt_i32_f32_e32 v154, v154
	v_cvt_i32_f32_e32 v155, v155
	v_perm_b32 v167, v155, v154, s85
	v_add_u32_e32 v154, v154, v155
	ds_write_b16 v90, v167 offset:3072
	s_nop 1
	v_add_u32_dpp v154, v154, v154 quad_perm:[1,0,3,2] row_mask:0xf bank_mask:0xf bound_ctrl:1
	s_nop 1
	v_add_u32_dpp v154, v154, v154 quad_perm:[2,3,0,1] row_mask:0xf bank_mask:0xf bound_ctrl:1
	s_nop 1
	v_add_u32_dpp v154, v154, v154 row_half_mirror row_mask:0xf bank_mask:0xf bound_ctrl:1
	s_nop 1
	v_add_u32_dpp v154, v154, v154 row_mirror row_mask:0xf bank_mask:0xf bound_ctrl:1
	s_nop 1
	v_readlane_b32 s46, v154, 0
	v_readlane_b32 s47, v154, 16
	v_readlane_b32 s12, v154, 32
	v_readlane_b32 s13, v154, 48
	s_nop 1
	s_add_i32 s46, s47, s46
	s_add_i32 s46, s46, s12
	s_add_i32 s46, s46, s13
	s_add_i32 s47, s67, 96
	s_and_saveexec_b64 s[12:13], s[8:9]
	v_mov_b32_e32 v154, s47
	v_mov_b32_e32 v155, s46
	ds_write2st64_b32 v154, v164, v155 offset1:1
	s_or_b64 exec, exec, s[12:13]
	s_waitcnt vmcnt(12)
	v_lshl_add_u32 v154, v34, 1, v62
	v_lshl_add_u32 v155, v35, 1, v62
	v_cvt_f32_i32_e32 v154, v154
	v_cvt_f32_i32_e32 v155, v155
	v_mul_f32_e32 v154, v126, v154
	v_mul_f32_e32 v155, v134, v155
	v_mul_f32_e32 v154, v70, v154
	v_mul_f32_e32 v155, v70, v155
	v_mul_f32_e64 v156, |v154|, s82
	v_mul_f32_e64 v157, |v155|, s82
	v_fma_f32 v158, v156, s83, 1.0
	v_fma_f32 v159, v157, s83, 1.0
	v_rcp_f32_e32 v158, v158
	v_rcp_f32_e32 v159, v159
	v_mul_f32_e64 v156, v156, -v156
	v_mul_f32_e64 v157, v157, -v157
	v_mul_f32_e32 v156, 0x3fb8aa3b, v156
	v_mul_f32_e32 v157, 0x3fb8aa3b, v157
	v_fmamk_f32 v160, v158, 0x3f87dc22, v110
	v_fmamk_f32 v161, v159, 0x3f87dc22, v110
	v_exp_f32_e32 v156, v156
	v_exp_f32_e32 v157, v157
	v_fmaak_f32 v160, v158, v160, 0x3fb5f0e3
	v_fmaak_f32 v161, v159, v161, 0x3fb5f0e3
	v_fmaak_f32 v160, v158, v160, 0xbe91a98e
	v_fmaak_f32 v161, v159, v161, 0xbe91a98e
	v_fmaak_f32 v160, v158, v160, 0x3e827906
	v_fmaak_f32 v161, v159, v161, 0x3e827906
	v_mul_f32_e32 v158, v158, v160
	v_mul_f32_e32 v159, v159, v161
	v_fma_f32 v156, -v156, v158, 1.0
	v_fma_f32 v157, -v157, v159, 1.0
	v_mul_f32_e32 v162, 0.5, v154
	v_mul_f32_e32 v163, 0.5, v155
	v_bfi_b32 v154, s84, v156, v154
	v_bfi_b32 v155, s84, v157, v155
	v_add_f32_e32 v154, 1.0, v154
	v_add_f32_e32 v155, 1.0, v155
	v_mul_f32_e32 v154, v162, v154
	v_mul_f32_e32 v155, v163, v155
	v_mul_f32_e32 v154, v50, v154
	v_mul_f32_e32 v155, v51, v155
	v_mul_f32_e32 v154, v150, v154
	v_mul_f32_e32 v155, v142, v155
	v_max_f32_e64 v164, |v154|, |v155|
	s_nop 1
	v_max_f32_dpp v164, v164, v164 quad_perm:[1,0,3,2] row_mask:0xf bank_mask:0xf
	s_nop 1
	v_max_f32_dpp v164, v164, v164 quad_perm:[2,3,0,1] row_mask:0xf bank_mask:0xf
	s_nop 1
	v_max_f32_dpp v164, v164, v164 row_half_mirror row_mask:0xf bank_mask:0xf
	s_nop 1
	v_max_f32_dpp v164, v164, v164 row_mirror row_mask:0xf bank_mask:0xf
	s_nop 1
	v_readlane_b32 s46, v164, 32
	v_readlane_b32 s47, v164, 48
; #define LAS __attribute__((address_space(3)))
; __global__ void __launch_bounds__(NTHR, 2) k_main(Args a) {
;     ...
;             for (int it = 0; it < 8; ++it) {
;                 const int tl = it * 8 + wave, t = j * 64 + tl;
;                 const unsigned ew = *(const LAS unsigned*)(EL + tl * 128 + 2 * lane); const int e0 = (int)(ew & 0xffffu), e1 = (int)(ew >> 16);
;                 typedef int i2v __attribute__((ext_vector_type(2))); const i2v si = *(const LAS i2v*)(ACC + tl * 128 + 2 * lane);
;                 typedef float f2v __attribute__((ext_vector_type(2))); const f2v gt = *(const LAS f2v*)(GL + tl * 128 + 2 * lane); const float xs = XS[t];
;                 const int sx = ((const int*)(XS + T))[t];
;                 const float z0 = (float)(2 * si.x + sx) * SU[e0] * xs, z1 = (float)(2 * si.y + sx) * SU[e1] * xs;
;                 const float a0 = gt.x * gelu_as(z0) * SV[e0], a1 = gt.y * gelu_as(z1) * SV[e1];
;                 const float mx = wave_max_dpp(fmaxf(fabsf(a0), fabsf(a1)));
;                 const float sc = mx > 0.f ? mx * (1.f / 119.f) : 1.f, inv = 1.f / sc;
;                 const int q0 = (int)rintf(a0 * inv), q1 = (int)rintf(a1 * inv);
;                 *(LAS unsigned short*)(AL + tl * 128 + 2 * lane) = (unsigned short)((q0 & 255) | ((q1 & 255) << 8));
;                 const int qs = wave_sum_dpp_i(q0 + q1);
;                 if (lane == 0) { ASC[tl] = sc; SAL[tl] = qs; }
;             }
	v_readlane_b32 s12, v164, 0
	v_readlane_b32 s13, v164, 16
	s_nop 1
	v_mov_b32_e32 v164, s47
	v_max_f32_e32 v164, s46, v164
	v_mov_b32_e32 v165, s13
	v_max3_f32 v164, s12, v165, v164
	v_mul_f32_e32 v165, 0x3c09ae41, v164
	v_cmp_lt_f32_e32 vcc, 0, v164
	s_nop 1
	v_cndmask_b32_e32 v164, 1.0, v165, vcc
	v_div_scale_f32 v166, s[12:13], v164, v164, 1.0
	v_rcp_f32_e32 v167, v166
	v_div_scale_f32 v168, vcc, 1.0, v164, 1.0
	v_fma_f32 v169, -v166, v167, 1.0
	v_fmac_f32_e32 v167, v169, v167
	v_mul_f32_e32 v169, v168, v167
	v_fma_f32 v170, -v166, v169, v168
	v_fmac_f32_e32 v169, v170, v167
	v_fma_f32 v166, -v166, v169, v168
	v_div_fmas_f32 v166, v166, v167, v169
	v_div_fixup_f32 v166, v166, v164, 1.0
	v_mul_f32_e32 v154, v166, v154
	v_mul_f32_e32 v155, v166, v155
	v_rndne_f32_e32 v154, v154
	v_rndne_f32_e32 v155, v155
	v_cvt_i32_f32_e32 v154, v154
	v_cvt_i32_f32_e32 v155, v155
	v_perm_b32 v167, v155, v154, s85
	v_add_u32_e32 v154, v154, v155
	ds_write_b16 v90, v167 offset:4096
	s_nop 1
	v_add_u32_dpp v154, v154, v154 quad_perm:[1,0,3,2] row_mask:0xf bank_mask:0xf bound_ctrl:1
	s_nop 1
	v_add_u32_dpp v154, v154, v154 quad_perm:[2,3,0,1] row_mask:0xf bank_mask:0xf bound_ctrl:1
	s_nop 1
	v_add_u32_dpp v154, v154, v154 row_half_mirror row_mask:0xf bank_mask:0xf bound_ctrl:1
	s_nop 1
	v_add_u32_dpp v154, v154, v154 row_mirror row_mask:0xf bank_mask:0xf bound_ctrl:1
	s_nop 1
	v_readlane_b32 s46, v154, 0
	v_readlane_b32 s47, v154, 16
	v_readlane_b32 s12, v154, 32
	v_readlane_b32 s13, v154, 48
	s_nop 1
	s_add_i32 s46, s47, s46
	s_add_i32 s46, s46, s12
	s_add_i32 s46, s46, s13
	s_add_i32 s47, s67, 128
	s_and_saveexec_b64 s[12:13], s[8:9]
	v_mov_b32_e32 v154, s47
	v_mov_b32_e32 v155, s46
	ds_write2st64_b32 v154, v164, v155 offset1:1
	s_or_b64 exec, exec, s[12:13]
	s_waitcnt vmcnt(8)
	v_lshl_add_u32 v154, v36, 1, v63
	v_lshl_add_u32 v155, v37, 1, v63
	v_cvt_f32_i32_e32 v154, v154
	v_cvt_f32_i32_e32 v155, v155
	v_mul_f32_e32 v154, v127, v154
	v_mul_f32_e32 v155, v135, v155
	v_mul_f32_e32 v154, v71, v154
	v_mul_f32_e32 v155, v71, v155
	v_mul_f32_e64 v156, |v154|, s82
	v_mul_f32_e64 v157, |v155|, s82
	v_fma_f32 v158, v156, s83, 1.0
	v_fma_f32 v159, v157, s83, 1.0
	v_rcp_f32_e32 v158, v158
	v_rcp_f32_e32 v159, v159
	v_mul_f32_e64 v156, v156, -v156
	v_mul_f32_e64 v157, v157, -v157
	v_mul_f32_e32 v156, 0x3fb8aa3b, v156
	v_mul_f32_e32 v157, 0x3fb8aa3b, v157
	v_fmamk_f32 v160, v158, 0x3f87dc22, v110
	v_fmamk_f32 v161, v159, 0x3f87dc22, v110
	v_exp_f32_e32 v156, v156
	v_exp_f32_e32 v157, v157
	v_fmaak_f32 v160, v158, v160, 0x3fb5f0e3
	v_fmaak_f32 v161, v159, v161, 0x3fb5f0e3
	v_fmaak_f32 v160, v158, v160, 0xbe91a98e
	v_fmaak_f32 v161, v159, v161, 0xbe91a98e
	v_fmaak_f32 v160, v158, v160, 0x3e827906
	v_fmaak_f32 v161, v159, v161, 0x3e827906
	v_mul_f32_e32 v158, v158, v160
	v_mul_f32_e32 v159, v159, v161
	v_fma_f32 v156, -v156, v158, 1.0
	v_fma_f32 v157, -v157, v159, 1.0
	v_mul_f32_e32 v162, 0.5, v154
	v_mul_f32_e32 v163, 0.5, v155
	v_bfi_b32 v154, s84, v156, v154
	v_bfi_b32 v155, s84, v157, v155
	v_add_f32_e32 v154, 1.0, v154
	v_add_f32_e32 v155, 1.0, v155
	v_mul_f32_e32 v154, v162, v154
	v_mul_f32_e32 v155, v163, v155
	v_mul_f32_e32 v154, v52, v154
	v_mul_f32_e32 v155, v53, v155
	v_mul_f32_e32 v154, v151, v154
	v_mul_f32_e32 v155, v143, v155
	v_max_f32_e64 v164, |v154|, |v155|
	s_nop 1
	v_max_f32_dpp v164, v164, v164 quad_perm:[1,0,3,2] row_mask:0xf bank_mask:0xf
	s_nop 1
	v_max_f32_dpp v164, v164, v164 quad_perm:[2,3,0,1] row_mask:0xf bank_mask:0xf
	s_nop 1
	v_max_f32_dpp v164, v164, v164 row_half_mirror row_mask:0xf bank_mask:0xf
	s_nop 1
	v_max_f32_dpp v164, v164, v164 row_mirror row_mask:0xf bank_mask:0xf
	s_nop 1
	v_readlane_b32 s46, v164, 32
	v_readlane_b32 s47, v164, 48
	v_readlane_b32 s12, v164, 0
	v_readlane_b32 s13, v164, 16
	s_nop 1
	v_mov_b32_e32 v164, s47
	v_max_f32_e32 v164, s46, v164
	v_mov_b32_e32 v165, s13
	v_max3_f32 v164, s12, v165, v164
	v_mul_f32_e32 v165, 0x3c09ae41, v164
	v_cmp_lt_f32_e32 vcc, 0, v164
	s_nop 1
	v_cndmask_b32_e32 v164, 1.0, v165, vcc
	v_div_scale_f32 v166, s[12:13], v164, v164, 1.0
	v_rcp_f32_e32 v167, v166
	v_div_scale_f32 v168, vcc, 1.0, v164, 1.0
	v_fma_f32 v169, -v166, v167, 1.0
	v_fmac_f32_e32 v167, v169, v167
	v_mul_f32_e32 v169, v168, v167
	v_fma_f32 v170, -v166, v169, v168
	v_fmac_f32_e32 v169, v170, v167
	v_fma_f32 v166, -v166, v169, v168
	v_div_fmas_f32 v166, v166, v167, v169
	v_div_fixup_f32 v166, v166, v164, 1.0
	v_mul_f32_e32 v154, v166, v154
	v_mul_f32_e32 v155, v166, v155
	v_rndne_f32_e32 v154, v154
	v_rndne_f32_e32 v155, v155
	v_cvt_i32_f32_e32 v154, v154
	v_cvt_i32_f32_e32 v155, v155
	v_perm_b32 v167, v155, v154, s85
	v_add_u32_e32 v154, v154, v155
	ds_write_b16 v90, v167 offset:5120
	s_nop 1
	v_add_u32_dpp v154, v154, v154 quad_perm:[1,0,3,2] row_mask:0xf bank_mask:0xf bound_ctrl:1
	s_nop 1
	v_add_u32_dpp v154, v154, v154 quad_perm:[2,3,0,1] row_mask:0xf bank_mask:0xf bound_ctrl:1
	s_nop 1
	v_add_u32_dpp v154, v154, v154 row_half_mirror row_mask:0xf bank_mask:0xf bound_ctrl:1
	s_nop 1
	v_add_u32_dpp v154, v154, v154 row_mirror row_mask:0xf bank_mask:0xf bound_ctrl:1
	s_nop 1
	v_readlane_b32 s46, v154, 0
	v_readlane_b32 s47, v154, 16
	v_readlane_b32 s12, v154, 32
	v_readlane_b32 s13, v154, 48
	s_nop 1
	s_add_i32 s46, s47, s46
	s_add_i32 s46, s46, s12
	s_add_i32 s46, s46, s13
	s_add_i32 s47, s67, 160
	s_and_saveexec_b64 s[12:13], s[8:9]
	v_mov_b32_e32 v154, s47
	v_mov_b32_e32 v155, s46
	ds_write2st64_b32 v154, v164, v155 offset1:1
	s_or_b64 exec, exec, s[12:13]
	s_waitcnt vmcnt(4)
; #define LAS __attribute__((address_space(3)))
; __global__ void __launch_bounds__(NTHR, 2) k_main(Args a) {
;     ...
;             for (int it = 0; it < 8; ++it) {
;                 const int tl = it * 8 + wave, t = j * 64 + tl;
;                 const unsigned ew = *(const LAS unsigned*)(EL + tl * 128 + 2 * lane); const int e0 = (int)(ew & 0xffffu), e1 = (int)(ew >> 16);
;                 typedef int i2v __attribute__((ext_vector_type(2))); const i2v si = *(const LAS i2v*)(ACC + tl * 128 + 2 * lane);
;                 typedef float f2v __attribute__((ext_vector_type(2))); const f2v gt = *(const LAS f2v*)(GL + tl * 128 + 2 * lane); const float xs = XS[t];
;                 const int sx = ((const int*)(XS + T))[t];
;                 const float z0 = (float)(2 * si.x + sx) * SU[e0] * xs, z1 = (float)(2 * si.y + sx) * SU[e1] * xs;
;                 const float a0 = gt.x * gelu_as(z0) * SV[e0], a1 = gt.y * gelu_as(z1) * SV[e1];
;                 const float mx = wave_max_dpp(fmaxf(fabsf(a0), fabsf(a1)));
;                 const float sc = mx > 0.f ? mx * (1.f / 119.f) : 1.f, inv = 1.f / sc;
;                 const int q0 = (int)rintf(a0 * inv), q1 = (int)rintf(a1 * inv);
;                 *(LAS unsigned short*)(AL + tl * 128 + 2 * lane) = (unsigned short)((q0 & 255) | ((q1 & 255) << 8));
;                 const int qs = wave_sum_dpp_i(q0 + q1);
;                 if (lane == 0) { ASC[tl] = sc; SAL[tl] = qs; }
;             }
	v_lshl_add_u32 v154, v38, 1, v64
	v_lshl_add_u32 v155, v39, 1, v64
	v_cvt_f32_i32_e32 v154, v154
	v_cvt_f32_i32_e32 v155, v155
	v_mul_f32_e32 v154, v128, v154
	v_mul_f32_e32 v155, v136, v155
	v_mul_f32_e32 v154, v72, v154
	v_mul_f32_e32 v155, v72, v155
	v_mul_f32_e64 v156, |v154|, s82
	v_mul_f32_e64 v157, |v155|, s82
	v_fma_f32 v158, v156, s83, 1.0
	v_fma_f32 v159, v157, s83, 1.0
	v_rcp_f32_e32 v158, v158
	v_rcp_f32_e32 v159, v159
	v_mul_f32_e64 v156, v156, -v156
	v_mul_f32_e64 v157, v157, -v157
	v_mul_f32_e32 v156, 0x3fb8aa3b, v156
	v_mul_f32_e32 v157, 0x3fb8aa3b, v157
	v_fmamk_f32 v160, v158, 0x3f87dc22, v110
	v_fmamk_f32 v161, v159, 0x3f87dc22, v110
	v_exp_f32_e32 v156, v156
	v_exp_f32_e32 v157, v157
	v_fmaak_f32 v160, v158, v160, 0x3fb5f0e3
	v_fmaak_f32 v161, v159, v161, 0x3fb5f0e3
	v_fmaak_f32 v160, v158, v160, 0xbe91a98e
	v_fmaak_f32 v161, v159, v161, 0xbe91a98e
	v_fmaak_f32 v160, v158, v160, 0x3e827906
	v_fmaak_f32 v161, v159, v161, 0x3e827906
	v_mul_f32_e32 v158, v158, v160
	v_mul_f32_e32 v159, v159, v161
	v_fma_f32 v156, -v156, v158, 1.0
	v_fma_f32 v157, -v157, v159, 1.0
	v_mul_f32_e32 v162, 0.5, v154
	v_mul_f32_e32 v163, 0.5, v155
	v_bfi_b32 v154, s84, v156, v154
	v_bfi_b32 v155, s84, v157, v155
	v_add_f32_e32 v154, 1.0, v154
	v_add_f32_e32 v155, 1.0, v155
	v_mul_f32_e32 v154, v162, v154
	v_mul_f32_e32 v155, v163, v155
	v_mul_f32_e32 v154, v54, v154
	v_mul_f32_e32 v155, v55, v155
	v_mul_f32_e32 v154, v152, v154
	v_mul_f32_e32 v155, v144, v155
	v_max_f32_e64 v164, |v154|, |v155|
	s_nop 1
	v_max_f32_dpp v164, v164, v164 quad_perm:[1,0,3,2] row_mask:0xf bank_mask:0xf
	s_nop 1
	v_max_f32_dpp v164, v164, v164 quad_perm:[2,3,0,1] row_mask:0xf bank_mask:0xf
	s_nop 1
	v_max_f32_dpp v164, v164, v164 row_half_mirror row_mask:0xf bank_mask:0xf
	s_nop 1
	v_max_f32_dpp v164, v164, v164 row_mirror row_mask:0xf bank_mask:0xf
	s_nop 1
	v_readlane_b32 s46, v164, 32
	v_readlane_b32 s47, v164, 48
	v_readlane_b32 s12, v164, 0
	v_readlane_b32 s13, v164, 16
	s_nop 1
	v_mov_b32_e32 v164, s47
	v_max_f32_e32 v164, s46, v164
	v_mov_b32_e32 v165, s13
	v_max3_f32 v164, s12, v165, v164
	v_mul_f32_e32 v165, 0x3c09ae41, v164
	v_cmp_lt_f32_e32 vcc, 0, v164
	s_nop 1
	v_cndmask_b32_e32 v164, 1.0, v165, vcc
	v_div_scale_f32 v166, s[12:13], v164, v164, 1.0
	v_rcp_f32_e32 v167, v166
	v_div_scale_f32 v168, vcc, 1.0, v164, 1.0
	v_fma_f32 v169, -v166, v167, 1.0
	v_fmac_f32_e32 v167, v169, v167
	v_mul_f32_e32 v169, v168, v167
	v_fma_f32 v170, -v166, v169, v168
	v_fmac_f32_e32 v169, v170, v167
	v_fma_f32 v166, -v166, v169, v168
	v_div_fmas_f32 v166, v166, v167, v169
	v_div_fixup_f32 v166, v166, v164, 1.0
	v_mul_f32_e32 v154, v166, v154
	v_mul_f32_e32 v155, v166, v155
	v_rndne_f32_e32 v154, v154
	v_rndne_f32_e32 v155, v155
	v_cvt_i32_f32_e32 v154, v154
	v_cvt_i32_f32_e32 v155, v155
	v_perm_b32 v167, v155, v154, s85
	v_add_u32_e32 v154, v154, v155
	ds_write_b16 v90, v167 offset:6144
	s_nop 1
	v_add_u32_dpp v154, v154, v154 quad_perm:[1,0,3,2] row_mask:0xf bank_mask:0xf bound_ctrl:1
	s_nop 1
	v_add_u32_dpp v154, v154, v154 quad_perm:[2,3,0,1] row_mask:0xf bank_mask:0xf bound_ctrl:1
	s_nop 1
	v_add_u32_dpp v154, v154, v154 row_half_mirror row_mask:0xf bank_mask:0xf bound_ctrl:1
	s_nop 1
	v_add_u32_dpp v154, v154, v154 row_mirror row_mask:0xf bank_mask:0xf bound_ctrl:1
	s_nop 1
	v_readlane_b32 s46, v154, 0
	v_readlane_b32 s47, v154, 16
	v_readlane_b32 s12, v154, 32
	v_readlane_b32 s13, v154, 48
	s_nop 1
	s_add_i32 s46, s47, s46
	s_add_i32 s46, s46, s12
	s_add_i32 s46, s46, s13
	s_add_i32 s47, s67, 192
	s_and_saveexec_b64 s[12:13], s[8:9]
	v_mov_b32_e32 v154, s47
	v_mov_b32_e32 v155, s46
	ds_write2st64_b32 v154, v164, v155 offset1:1
	s_or_b64 exec, exec, s[12:13]
	s_waitcnt vmcnt(0)
; #define LAS __attribute__((address_space(3)))
; __global__ void __launch_bounds__(NTHR, 2) k_main(Args a) {
;     ...
;             for (int it = 0; it < 8; ++it) {
;                 const int tl = it * 8 + wave, t = j * 64 + tl;
;                 const unsigned ew = *(const LAS unsigned*)(EL + tl * 128 + 2 * lane); const int e0 = (int)(ew & 0xffffu), e1 = (int)(ew >> 16);
;                 typedef int i2v __attribute__((ext_vector_type(2))); const i2v si = *(const LAS i2v*)(ACC + tl * 128 + 2 * lane);
;                 typedef float f2v __attribute__((ext_vector_type(2))); const f2v gt = *(const LAS f2v*)(GL + tl * 128 + 2 * lane); const float xs = XS[t];
;                 const int sx = ((const int*)(XS + T))[t];
;                 const float z0 = (float)(2 * si.x + sx) * SU[e0] * xs, z1 = (float)(2 * si.y + sx) * SU[e1] * xs;
;                 const float a0 = gt.x * gelu_as(z0) * SV[e0], a1 = gt.y * gelu_as(z1) * SV[e1];
;                 const float mx = wave_max_dpp(fmaxf(fabsf(a0), fabsf(a1)));
;                 const float sc = mx > 0.f ? mx * (1.f / 119.f) : 1.f, inv = 1.f / sc;
;                 const int q0 = (int)rintf(a0 * inv), q1 = (int)rintf(a1 * inv);
;                 *(LAS unsigned short*)(AL + tl * 128 + 2 * lane) = (unsigned short)((q0 & 255) | ((q1 & 255) << 8));
;                 const int qs = wave_sum_dpp_i(q0 + q1);
;                 if (lane == 0) { ASC[tl] = sc; SAL[tl] = qs; }
;             }
	v_lshl_add_u32 v154, v40, 1, v65
	v_lshl_add_u32 v155, v41, 1, v65
	v_cvt_f32_i32_e32 v154, v154
	v_cvt_f32_i32_e32 v155, v155
	v_mul_f32_e32 v154, v129, v154
	v_mul_f32_e32 v155, v137, v155
	v_mul_f32_e32 v154, v73, v154
	v_mul_f32_e32 v155, v73, v155
	v_mul_f32_e64 v156, |v154|, s82
	v_mul_f32_e64 v157, |v155|, s82
	v_fma_f32 v158, v156, s83, 1.0
	v_fma_f32 v159, v157, s83, 1.0
	v_rcp_f32_e32 v158, v158
	v_rcp_f32_e32 v159, v159
	v_mul_f32_e64 v156, v156, -v156
	v_mul_f32_e64 v157, v157, -v157
	v_mul_f32_e32 v156, 0x3fb8aa3b, v156
	v_mul_f32_e32 v157, 0x3fb8aa3b, v157
	v_fmamk_f32 v160, v158, 0x3f87dc22, v110
	v_fmamk_f32 v161, v159, 0x3f87dc22, v110
	v_exp_f32_e32 v156, v156
	v_exp_f32_e32 v157, v157
	v_fmaak_f32 v160, v158, v160, 0x3fb5f0e3
	v_fmaak_f32 v161, v159, v161, 0x3fb5f0e3
	v_fmaak_f32 v160, v158, v160, 0xbe91a98e
	v_fmaak_f32 v161, v159, v161, 0xbe91a98e
	v_fmaak_f32 v160, v158, v160, 0x3e827906
	v_fmaak_f32 v161, v159, v161, 0x3e827906
	v_mul_f32_e32 v158, v158, v160
	v_mul_f32_e32 v159, v159, v161
	v_fma_f32 v156, -v156, v158, 1.0
	v_fma_f32 v157, -v157, v159, 1.0
	v_mul_f32_e32 v162, 0.5, v154
	v_mul_f32_e32 v163, 0.5, v155
	v_bfi_b32 v154, s84, v156, v154
	v_bfi_b32 v155, s84, v157, v155
	v_add_f32_e32 v154, 1.0, v154
	v_add_f32_e32 v155, 1.0, v155
	v_mul_f32_e32 v154, v162, v154
	v_mul_f32_e32 v155, v163, v155
	v_mul_f32_e32 v154, v56, v154
	v_mul_f32_e32 v155, v57, v155
	v_mul_f32_e32 v154, v153, v154
	v_mul_f32_e32 v155, v145, v155
	v_max_f32_e64 v164, |v154|, |v155|
	s_nop 1
	v_max_f32_dpp v164, v164, v164 quad_perm:[1,0,3,2] row_mask:0xf bank_mask:0xf
	s_nop 1
	v_max_f32_dpp v164, v164, v164 quad_perm:[2,3,0,1] row_mask:0xf bank_mask:0xf
	s_nop 1
	v_max_f32_dpp v164, v164, v164 row_half_mirror row_mask:0xf bank_mask:0xf
	s_nop 1
	v_max_f32_dpp v164, v164, v164 row_mirror row_mask:0xf bank_mask:0xf
	s_nop 1
	v_readlane_b32 s46, v164, 32
	v_readlane_b32 s47, v164, 48
	v_readlane_b32 s12, v164, 0
	v_readlane_b32 s13, v164, 16
	s_nop 1
	v_mov_b32_e32 v164, s47
	v_max_f32_e32 v164, s46, v164
	v_mov_b32_e32 v165, s13
	v_max3_f32 v164, s12, v165, v164
	v_mul_f32_e32 v165, 0x3c09ae41, v164
	v_cmp_lt_f32_e32 vcc, 0, v164
	s_nop 1
	v_cndmask_b32_e32 v164, 1.0, v165, vcc
	v_div_scale_f32 v166, s[12:13], v164, v164, 1.0
	v_rcp_f32_e32 v167, v166
	v_div_scale_f32 v168, vcc, 1.0, v164, 1.0
	v_fma_f32 v169, -v166, v167, 1.0
	v_fmac_f32_e32 v167, v169, v167
	v_mul_f32_e32 v169, v168, v167
	v_fma_f32 v170, -v166, v169, v168
	v_fmac_f32_e32 v169, v170, v167
	v_fma_f32 v166, -v166, v169, v168
	v_div_fmas_f32 v166, v166, v167, v169
	v_div_fixup_f32 v166, v166, v164, 1.0
	v_mul_f32_e32 v154, v166, v154
	v_mul_f32_e32 v155, v166, v155
	v_rndne_f32_e32 v154, v154
	v_rndne_f32_e32 v155, v155
	v_cvt_i32_f32_e32 v154, v154
	v_cvt_i32_f32_e32 v155, v155
	v_perm_b32 v167, v155, v154, s85
	v_add_u32_e32 v154, v154, v155
	ds_write_b16 v90, v167 offset:7168
	s_nop 1
	v_add_u32_dpp v154, v154, v154 quad_perm:[1,0,3,2] row_mask:0xf bank_mask:0xf bound_ctrl:1
	s_nop 1
	v_add_u32_dpp v154, v154, v154 quad_perm:[2,3,0,1] row_mask:0xf bank_mask:0xf bound_ctrl:1
	s_nop 1
	v_add_u32_dpp v154, v154, v154 row_half_mirror row_mask:0xf bank_mask:0xf bound_ctrl:1
	s_nop 1
	v_add_u32_dpp v154, v154, v154 row_mirror row_mask:0xf bank_mask:0xf bound_ctrl:1
	s_nop 1
	v_readlane_b32 s46, v154, 0
	v_readlane_b32 s47, v154, 16
	v_readlane_b32 s12, v154, 32
	v_readlane_b32 s13, v154, 48
	s_nop 1
	s_add_i32 s46, s47, s46
	s_add_i32 s46, s46, s12
	s_add_i32 s46, s46, s13
	s_add_i32 s47, s67, 224
	s_and_saveexec_b64 s[12:13], s[8:9]
	v_mov_b32_e32 v154, s47
	v_mov_b32_e32 v155, s46
	ds_write2st64_b32 v154, v164, v155 offset1:1
	s_or_b64 exec, exec, s[12:13]
